# v91 + attention loops: V^T LDS base computed with one v_add3_u32 instead of two adds
# speedup vs baseline: 1.0007x; 1.0007x over previous
; #define LAS __attribute__((address_space(3)))
; DI float shfl_xor_l(float v, int lane, int m) { return __int_as_float(__builtin_amdgcn_ds_bpermute((lane ^ m) << 2, __float_as_int(v))); }
; #define A_LOAD(kt) do { const size_t ko = (size_t)(kt) * 64; st0 = *(const u32x4*)(kn_src + ko * 2048); st1 = *(const u32x4*)(kn_src + (ko + 32) * 2048); \
;         st2 = *(const u32x4*)(kr_src + ko * 64); st3 = *(const u32x4*)(v_src + ko); st4 = *(const u32x4*)(v_src + ko + (size_t)64 * 8192); } while (0)
; #define VLD(dst, j, dt) do { LAS unsigned char* va_ = vb + (32 * (dt) + n) * VROW + (16 * (j) + 4 * g) * 2; const u32x2 lo_ = *(const LAS u32x2*)(va_), hi_ = *(const LAS u32x2*)(va_ + 16); dst = (u32x4){lo_.x, lo_.y, hi_.x, hi_.y}; } while (0)
; DI void attn_unit(LAS unsigned char* lds, int wid, int b, int h, int qb) {
;     ...
;     for (int kt = 0; kt < nkt; ++kt) {
;         const int buf = kt & 1;
;         if (kt + 1 < nkt) A_LOAD(kt + 1);
;         if (kt <= cq) {
;             LAS unsigned char* kb = lds + buf * ABUF; LAS unsigned char* vb = kb + KBYTES;
;             f32x16 s0, s1;
; #pragma unroll
;             for (int i = 0; i < 16; ++i) { s0[i] = 0.f; s1[i] = 0.f; }
;     ...
;             bf16x8 ka[3][2];
;             ka[0][0] = KLD(0, 0); ka[0][1] = KLD(0, 1); ka[1][0] = KLD(1, 0); ka[1][1] = KLD(1, 1);
; #pragma unroll
;             for (int ks = 0; ks < 12; ++ks) {
;                 if (ks + 2 < 12) { ka[(ks + 2) % 3][0] = KLD(ks + 2, 0); ka[(ks + 2) % 3][1] = KLD(ks + 2, 1); }
;                 s0 = __builtin_amdgcn_mfma_f32_32x32x16_bf16(ka[ks % 3][0], qf[ks], s0, 0, 0, 0); s1 = __builtin_amdgcn_mfma_f32_32x32x16_bf16(ka[ks % 3][1], qf[ks], s1, 0, 0, 0);
;                 __builtin_amdgcn_sched_barrier(0); }
;             u32x4 vf[2][4];
; #pragma unroll
;             for (int dt = 0; dt < 4; ++dt) VLD(vf[0][dt], 0, dt);
;             float mx = s0[0];
; #pragma unroll
;             for (int i = 1; i < 16; ++i) mx = fmaxf(mx, s0[i]);
; #pragma unroll
;             for (int i = 0; i < 16; ++i) mx = fmaxf(mx, s1[i]);
;             mx = fmaxf(mx, shfl_xor_l(mx, lane, 32));
.LBB0_1079:
	s_and_b32 s65, s64, 1
	global_load_dwordx4 v[146:149], v194, s[70:71]
	global_load_dwordx4 v[150:153], v194, s[72:73]
	global_load_dwordx4 v[154:157], v192, s[78:79]
	global_load_dwordx4 v[158:161], v190, s[74:75] offset:128
	global_load_dwordx4 v[162:165], v190, s[76:77] offset:128
	s_cmp_gt_u32 s64, s62
	s_cbranch_scc1 .LBB0_1083
	s_mul_i32 s66, s65, 0xa800
	s_add_i32 s66, s66, 0
	v_add3_u32 v171, s66, v199, v202
	ds_read_b128 v[66:69], v171
	ds_read_b128 v[166:169], v171 offset:32
	ds_read_b128 v[82:85], v171 offset:12800
	ds_read_b128 v[172:175], v171 offset:64
	ds_read_b128 v[176:179], v171 offset:12832
	ds_read_b128 v[204:207], v171 offset:12864
	s_waitcnt lgkmcnt(3)
	v_mfma_f32_32x32x16_bf16 v[82:97], v[82:85], v[142:145], v[216:231]
	v_mfma_f32_32x32x16_bf16 v[66:81], v[66:69], v[142:145], v[216:231]
	v_mfma_f32_32x32x16_bf16 v[66:81], v[166:169], v[138:141], v[66:81]
	ds_read_b128 v[166:169], v171 offset:96
	ds_read_b128 v[208:211], v171 offset:12896
	s_waitcnt lgkmcnt(3)
	v_mfma_f32_32x32x16_bf16 v[82:97], v[176:179], v[138:141], v[82:97]
	v_mfma_f32_32x32x16_bf16 v[66:81], v[172:175], v[134:137], v[66:81]
	ds_read_b128 v[172:175], v171 offset:128
	ds_read_b128 v[176:179], v171 offset:12928
	s_waitcnt lgkmcnt(4)
	v_mfma_f32_32x32x16_bf16 v[82:97], v[204:207], v[134:137], v[82:97]
	s_waitcnt lgkmcnt(3)
	v_mfma_f32_32x32x16_bf16 v[66:81], v[166:169], v[130:133], v[66:81]
	ds_read_b128 v[166:169], v171 offset:160
	ds_read_b128 v[204:207], v171 offset:12960
	s_waitcnt lgkmcnt(4)
	v_mfma_f32_32x32x16_bf16 v[82:97], v[208:211], v[130:133], v[82:97]
	s_waitcnt lgkmcnt(3)
	v_mfma_f32_32x32x16_bf16 v[66:81], v[172:175], v[126:129], v[66:81]
	ds_read_b128 v[172:175], v171 offset:192
	ds_read_b128 v[208:211], v171 offset:12992
	s_waitcnt lgkmcnt(4)
	v_mfma_f32_32x32x16_bf16 v[82:97], v[176:179], v[126:129], v[82:97]
	s_waitcnt lgkmcnt(3)
	v_mfma_f32_32x32x16_bf16 v[66:81], v[166:169], v[122:125], v[66:81]
	ds_read_b128 v[166:169], v171 offset:224
	ds_read_b128 v[176:179], v171 offset:13024
	s_waitcnt lgkmcnt(4)
	v_mfma_f32_32x32x16_bf16 v[82:97], v[204:207], v[122:125], v[82:97]
	s_waitcnt lgkmcnt(3)
	v_mfma_f32_32x32x16_bf16 v[66:81], v[172:175], v[118:121], v[66:81]
	ds_read_b128 v[172:175], v171 offset:256
	ds_read_b128 v[204:207], v171 offset:13056
	s_waitcnt lgkmcnt(4)
	v_mfma_f32_32x32x16_bf16 v[82:97], v[208:211], v[118:121], v[82:97]
	s_waitcnt lgkmcnt(3)
	v_mfma_f32_32x32x16_bf16 v[66:81], v[166:169], v[114:117], v[66:81]
	ds_read_b128 v[166:169], v171 offset:288
	ds_read_b128 v[208:211], v171 offset:13088
	s_waitcnt lgkmcnt(4)
	v_mfma_f32_32x32x16_bf16 v[82:97], v[176:179], v[114:117], v[82:97]
	s_waitcnt lgkmcnt(3)
	v_mfma_f32_32x32x16_bf16 v[66:81], v[172:175], v[110:113], v[66:81]
	ds_read_b128 v[172:175], v171 offset:320
	ds_read_b128 v[176:179], v171 offset:13120
	s_waitcnt lgkmcnt(4)
	v_mfma_f32_32x32x16_bf16 v[82:97], v[204:207], v[110:113], v[82:97]
	s_waitcnt lgkmcnt(3)
	v_mfma_f32_32x32x16_bf16 v[66:81], v[166:169], v[106:109], v[66:81]
	ds_read_b128 v[166:169], v171 offset:352
	ds_read_b128 v[212:215], v171 offset:13152
	s_waitcnt lgkmcnt(4)
	v_mfma_f32_32x32x16_bf16 v[82:97], v[208:211], v[106:109], v[82:97]
	s_waitcnt lgkmcnt(3)
	v_mfma_f32_32x32x16_bf16 v[66:81], v[172:175], v[102:105], v[66:81]
	s_waitcnt lgkmcnt(2)
	v_mfma_f32_32x32x16_bf16 v[82:97], v[176:179], v[102:105], v[82:97]
	s_waitcnt lgkmcnt(1)
	v_mfma_f32_32x32x16_bf16 v[66:81], v[166:169], v[98:101], v[66:81]
	v_add3_u32 v171, s66, v184, v189
	v_add_u32_e32 v204, 0x6000, v171
	v_add_u32_e32 v205, 0x7000, v171
	v_add_u32_e32 v206, 0x8000, v171
	v_add_u32_e32 v207, 0x9000, v171
	ds_read2_b64 v[166:169], v204 offset0:128 offset1:130
	s_nop 4
	v_max_f32_e32 v172, v66, v67
	s_waitcnt lgkmcnt(1)
	v_mfma_f32_32x32x16_bf16 v[82:97], v[212:215], v[98:101], v[82:97]
	v_max3_f32 v172, v172, v68, v69
	v_max3_f32 v172, v172, v70, v71
	v_max3_f32 v172, v172, v72, v73
	v_max3_f32 v172, v172, v74, v75
	v_max3_f32 v172, v172, v76, v77
	v_max3_f32 v172, v172, v78, v79
	v_max3_f32 v172, v172, v80, v81
	s_nop 4
	v_max3_f32 v172, v172, v82, v83
	v_max3_f32 v172, v172, v84, v85
	v_max3_f32 v172, v172, v86, v87
	v_max3_f32 v172, v172, v88, v89
	v_max3_f32 v172, v172, v90, v91
	v_max3_f32 v172, v172, v92, v93
	v_max3_f32 v172, v172, v94, v95
	v_max3_f32 v172, v172, v96, v97
	ds_read2_b64 v[178:181], v205 offset0:160 offset1:162
	ds_read2_b64 v[174:177], v206 offset0:192 offset1:194
	v_cmp_lt_f32_e32 vcc, 0x41000000, v172
	s_cmp_eq_u32 s64, 0
	s_cbranch_scc1 .Lfold_0_upd
	s_cbranch_vccnz .Lfold_0_upd

; #define LAS __attribute__((address_space(3)))
; DI float shfl_xor_l(float v, int lane, int m) { return __int_as_float(__builtin_amdgcn_ds_bpermute((lane ^ m) << 2, __float_as_int(v))); }
; #define A_LOAD(kt) do { const size_t ko = (size_t)(kt) * 64; st0 = *(const u32x4*)(kn_src + ko * 2048); st1 = *(const u32x4*)(kn_src + (ko + 32) * 2048); \
;         st2 = *(const u32x4*)(kr_src + ko * 64); st3 = *(const u32x4*)(v_src + ko); st4 = *(const u32x4*)(v_src + ko + (size_t)64 * 8192); } while (0)
; #define VLD(dst, j, dt) do { LAS unsigned char* va_ = vb + (32 * (dt) + n) * VROW + (16 * (j) + 4 * g) * 2; const u32x2 lo_ = *(const LAS u32x2*)(va_), hi_ = *(const LAS u32x2*)(va_ + 16); dst = (u32x4){lo_.x, lo_.y, hi_.x, hi_.y}; } while (0)
; DI void attn_unit(LAS unsigned char* lds, int wid, int b, int h, int qb) {
;     ...
;     for (int kt = 0; kt < nkt; ++kt) {
;         const int buf = kt & 1;
;         if (kt + 1 < nkt) A_LOAD(kt + 1);
;         if (kt <= cq) {
;             LAS unsigned char* kb = lds + buf * ABUF; LAS unsigned char* vb = kb + KBYTES;
;             f32x16 s0, s1;
; #pragma unroll
;             for (int i = 0; i < 16; ++i) { s0[i] = 0.f; s1[i] = 0.f; }
;     ...
;             bf16x8 ka[3][2];
;             ka[0][0] = KLD(0, 0); ka[0][1] = KLD(0, 1); ka[1][0] = KLD(1, 0); ka[1][1] = KLD(1, 1);
; #pragma unroll
;             for (int ks = 0; ks < 12; ++ks) {
;                 if (ks + 2 < 12) { ka[(ks + 2) % 3][0] = KLD(ks + 2, 0); ka[(ks + 2) % 3][1] = KLD(ks + 2, 1); }
;                 s0 = __builtin_amdgcn_mfma_f32_32x32x16_bf16(ka[ks % 3][0], qf[ks], s0, 0, 0, 0); s1 = __builtin_amdgcn_mfma_f32_32x32x16_bf16(ka[ks % 3][1], qf[ks], s1, 0, 0, 0);
;                 __builtin_amdgcn_sched_barrier(0); }
;             u32x4 vf[2][4];
; #pragma unroll
;             for (int dt = 0; dt < 4; ++dt) VLD(vf[0][dt], 0, dt);
;             float mx = s0[0];
; #pragma unroll
;             for (int i = 1; i < 16; ++i) mx = fmaxf(mx, s0[i]);
; #pragma unroll
;             for (int i = 0; i < 16; ++i) mx = fmaxf(mx, s1[i]);
;             mx = fmaxf(mx, shfl_xor_l(mx, lane, 32));
.LBB0_1091:
	s_and_b32 s18, s57, 1
	global_load_dwordx4 v[2:5], v198, s[70:71]
	global_load_dwordx4 v[6:9], v198, s[72:73]
	global_load_dwordx4 v[10:13], v196, s[78:79]
	global_load_dwordx4 v[160:163], v194, s[74:75] offset:128
	global_load_dwordx4 v[164:167], v194, s[76:77] offset:128
	s_cmp_gt_u32 s57, s25
	s_cbranch_scc1 .LBB0_1095
	s_mul_i32 s19, s18, 0xa800
	s_add_i32 s19, s19, 0
	v_add3_u32 v0, s19, v193, v204
	ds_read_b128 v[80:83], v0
	ds_read_b128 v[168:171], v0 offset:32
	ds_read_b128 v[96:99], v0 offset:12800
	ds_read_b128 v[174:177], v0 offset:64
	ds_read_b128 v[178:181], v0 offset:12832
	ds_read_b128 v[206:209], v0 offset:12864
	s_waitcnt vmcnt(6) lgkmcnt(3)
	v_mfma_f32_32x32x16_bf16 v[96:111], v[96:99], v[156:159], v[216:231]
	v_mfma_f32_32x32x16_bf16 v[80:95], v[80:83], v[156:159], v[216:231]
	v_mfma_f32_32x32x16_bf16 v[80:95], v[168:171], v[152:155], v[80:95]
	ds_read_b128 v[168:171], v0 offset:96
	ds_read_b128 v[210:213], v0 offset:12896
	s_waitcnt lgkmcnt(3)
	v_mfma_f32_32x32x16_bf16 v[96:111], v[178:181], v[152:155], v[96:111]
	v_mfma_f32_32x32x16_bf16 v[80:95], v[174:177], v[148:151], v[80:95]
	ds_read_b128 v[174:177], v0 offset:128
	ds_read_b128 v[178:181], v0 offset:12928
	s_waitcnt lgkmcnt(4)
	v_mfma_f32_32x32x16_bf16 v[96:111], v[206:209], v[148:151], v[96:111]
	s_waitcnt lgkmcnt(3)
	v_mfma_f32_32x32x16_bf16 v[80:95], v[168:171], v[144:147], v[80:95]
	ds_read_b128 v[168:171], v0 offset:160
	ds_read_b128 v[206:209], v0 offset:12960
	s_waitcnt lgkmcnt(4)
	v_mfma_f32_32x32x16_bf16 v[96:111], v[210:213], v[144:147], v[96:111]
	s_waitcnt lgkmcnt(3)
	v_mfma_f32_32x32x16_bf16 v[80:95], v[174:177], v[140:143], v[80:95]
	ds_read_b128 v[174:177], v0 offset:192
	ds_read_b128 v[210:213], v0 offset:12992
	s_waitcnt lgkmcnt(4)
	v_mfma_f32_32x32x16_bf16 v[96:111], v[178:181], v[140:143], v[96:111]
	s_waitcnt lgkmcnt(3)
	v_mfma_f32_32x32x16_bf16 v[80:95], v[168:171], v[136:139], v[80:95]
	ds_read_b128 v[168:171], v0 offset:224
	ds_read_b128 v[178:181], v0 offset:13024
	s_waitcnt lgkmcnt(4)
	v_mfma_f32_32x32x16_bf16 v[96:111], v[206:209], v[136:139], v[96:111]
	s_waitcnt lgkmcnt(3)
	v_mfma_f32_32x32x16_bf16 v[80:95], v[174:177], v[132:135], v[80:95]
	ds_read_b128 v[174:177], v0 offset:256
	ds_read_b128 v[206:209], v0 offset:13056
	s_waitcnt lgkmcnt(4)
	v_mfma_f32_32x32x16_bf16 v[96:111], v[210:213], v[132:135], v[96:111]
	s_waitcnt lgkmcnt(3)
	v_mfma_f32_32x32x16_bf16 v[80:95], v[168:171], v[128:131], v[80:95]
	ds_read_b128 v[168:171], v0 offset:288
	ds_read_b128 v[210:213], v0 offset:13088
	s_waitcnt lgkmcnt(4)
	v_mfma_f32_32x32x16_bf16 v[96:111], v[178:181], v[128:131], v[96:111]
	s_waitcnt lgkmcnt(3)
	v_mfma_f32_32x32x16_bf16 v[80:95], v[174:177], v[124:127], v[80:95]
	ds_read_b128 v[174:177], v0 offset:320
	ds_read_b128 v[178:181], v0 offset:13120
	s_waitcnt lgkmcnt(4)
	v_mfma_f32_32x32x16_bf16 v[96:111], v[206:209], v[124:127], v[96:111]
	s_waitcnt lgkmcnt(3)
	v_mfma_f32_32x32x16_bf16 v[80:95], v[168:171], v[120:123], v[80:95]
	ds_read_b128 v[168:171], v0 offset:352
	ds_read_b128 v[206:209], v0 offset:13152
	s_waitcnt lgkmcnt(4)
	v_mfma_f32_32x32x16_bf16 v[96:111], v[210:213], v[120:123], v[96:111]
	s_waitcnt lgkmcnt(3)
	v_mfma_f32_32x32x16_bf16 v[80:95], v[174:177], v[116:119], v[80:95]
	s_waitcnt lgkmcnt(2)
	v_mfma_f32_32x32x16_bf16 v[96:111], v[178:181], v[116:119], v[96:111]
	s_waitcnt vmcnt(5) lgkmcnt(1)
	v_mfma_f32_32x32x16_bf16 v[80:95], v[168:171], v[112:115], v[80:95]
	v_add3_u32 v173, s19, v188, v191
	v_add_u32_e32 v15, 0x6000, v173
	v_add_u32_e32 v205, 0x7000, v173
	ds_read2_b64 v[168:171], v15 offset0:128 offset1:130
	ds_read2_b64 v[180:183], v205 offset0:160 offset1:162
	s_nop 5
	v_max_f32_e32 v0, v80, v81
	s_waitcnt lgkmcnt(2)
	v_mfma_f32_32x32x16_bf16 v[96:111], v[206:209], v[112:115], v[96:111]
	v_max3_f32 v0, v0, v82, v83
	v_max3_f32 v0, v0, v84, v85
	v_max3_f32 v0, v0, v86, v87
	v_max3_f32 v0, v0, v88, v89
	v_max3_f32 v0, v0, v90, v91
	v_max3_f32 v0, v0, v92, v93
	v_max3_f32 v0, v0, v94, v95
	s_nop 4
	v_max3_f32 v0, v0, v96, v97
	v_max3_f32 v0, v0, v98, v99
	v_max3_f32 v0, v0, v100, v101
	v_max3_f32 v0, v0, v102, v103
	v_max3_f32 v0, v0, v104, v105
	v_max3_f32 v0, v0, v106, v107
	v_max3_f32 v0, v0, v108, v109
	v_max3_f32 v0, v0, v110, v111
	v_add_u32_e32 v206, 0x8000, v173
	v_add_u32_e32 v207, 0x9000, v173
	ds_read2_b64 v[176:179], v206 offset0:192 offset1:194
	v_cmp_lt_f32_e32 vcc, 0x41000000, v0
	ds_read2_b64 v[172:175], v207 offset0:224 offset1:226
	s_cmp_eq_u32 s57, 0
	s_cbranch_scc1 .Lfold_2_upd
	s_cbranch_vccnz .Lfold_2_upd
